# S5 latent scans: each unit split over two waves on different SIMDs (state halves A/B, LDS image shared, one s_barrier per chunk), latent units spread over 64 WGs, ctx units moved to idle WGs
# speedup vs baseline: 1.0573x; 1.0189x over previous
.LBB0_88:
	s_andn2_b64 vcc, exec, s[2:3]
	s_cbranch_vccnz .LBB0_109
	s_movk_i32 s2, 0x180
	v_cmp_gt_i32_e32 vcc, s2, v132
	s_and_saveexec_b64 s[46:47], vcc
	s_cbranch_execz .LBB0_108
	v_mov_b32_e32 v211, v134
	v_readfirstlane_b32 s60, v132
	s_cmpk_lt_u32 s60, 0x80
	s_cbranch_scc0 .LS5R_nomap
	s_bitcmp1_b32 s60, 0
	s_cbranch_scc0 .LS5R_lat
	s_movk_i32 s61, 0x100
.LS5R_hl:
	s_barrier
	s_sub_u32 s61, s61, 1
	s_cmp_lg_u32 s61, 0
	s_cbranch_scc1 .LS5R_hl
	s_branch .LBB0_108
.LS5R_lat:
	v_lshrrev_b32_e32 v211, 7, v134
	s_and_b32 s61, s60, 2
	v_and_b32_e32 v0, 63, v134
	v_or_b32_e32 v211, s61, v211
	v_lshl_or_b32 v211, v211, 6, v0
.LS5R_nomap:
	s_waitcnt vmcnt(5)
	v_bfe_u32 v4, v211, 6, 1
	v_lshrrev_b32_e32 v133, 6, v211
	s_movk_i32 s2, 0x2200
	v_or_b32_e32 v2, s81, v4
	v_lshrrev_b32_e32 v0, 1, v203
	v_and_b32_e32 v3, 3, v203
	v_mad_u32_u24 v5, v133, s2, v135
	s_waitcnt vmcnt(4)
	v_and_b32_e32 v8, 31, v203
	v_and_or_b32 v205, v0, 12, v3
	v_ashrrev_i32_e32 v3, 31, v2
	s_mov_b32 s2, 0x3000000
	v_bfe_u32 v141, v203, 5, 1
	v_lshlrev_b32_e32 v206, 6, v2
	v_lshlrev_b64 v[136:137], 12, v[2:3]
	v_lshl_or_b32 v138, v4, 13, v8
	v_mul_lo_u32 v2, v4, s2
	v_cmp_eq_u32_e64 s[40:41], 0, v4
	v_and_b32_e32 v4, 64, v211
	s_waitcnt vmcnt(3)
	v_and_b32_e32 v10, 15, v203
	v_cmp_ne_u32_e64 s[42:43], 0, v4
	v_mul_u32_u24_e32 v4, 0x1100, v141
	v_lshlrev_b32_e32 v7, 2, v8
	v_lshrrev_b32_e32 v6, 2, v203
	v_add3_u32 v207, v5, v4, v7
	v_mul_u32_u24_e32 v7, 0x110, v10
	v_and_b32_e32 v4, 48, v203
	v_readlane_b32 s4, v253, 33
	v_add3_u32 v208, v5, v7, v4
	v_and_b32_e32 v140, 12, v6
	v_lshlrev_b32_e32 v6, 4, v141
	v_mov_b32_e32 v7, v1
	v_readlane_b32 s16, v253, 45
	v_readlane_b32 s17, v253, 46
	v_or_b32_e32 v136, v136, v8
	v_readlane_b32 s5, v253, 34
	v_readlane_b32 s6, v253, 35
	v_readlane_b32 s7, v253, 36
	v_lshl_add_u64 v[6:7], s[16:17], 0, v[6:7]
	v_lshlrev_b32_e32 v8, 5, v8
	v_mov_b32_e32 v9, v1
	v_readlane_b32 s18, v253, 47
	v_readlane_b32 s19, v253, 48
	v_lshl_add_u64 v[142:143], v[6:7], 0, v[8:9]
	v_lshlrev_b32_e32 v6, 8, v10
	v_mov_b32_e32 v7, v1
	v_readlane_b32 s4, v252, 40
	v_mov_b32_e32 v3, v1
	v_lshl_add_u64 v[6:7], s[18:19], 0, v[6:7]
	v_mov_b32_e32 v5, v1
	v_readlane_b32 s5, v252, 41
	v_lshlrev_b32_e32 v0, 3, v141
	v_lshl_add_u64 v[144:145], v[6:7], 0, v[4:5]
	v_lshl_add_u64 v[2:3], s[4:5], 0, v[2:3]
	v_lshlrev_b32_e32 v4, 2, v10
	v_bfe_u32 v204, v203, 2, 1
	v_mov_b32_e32 v139, v1
	v_lshl_add_u64 v[146:147], v[2:3], 0, v[4:5]
	s_mov_b64 s[48:49], 0
	v_lshlrev_b32_e32 v148, 2, v0
	v_mov_b32_e32 v209, v132
	v_readlane_b32 s8, v253, 37
	v_readlane_b32 s9, v253, 38
	v_readlane_b32 s10, v253, 39
	v_readlane_b32 s11, v253, 40
	v_readlane_b32 s12, v253, 41
	v_readlane_b32 s13, v253, 42
	v_readlane_b32 s14, v253, 43
	v_readlane_b32 s15, v253, 44
	v_readlane_b32 s6, v252, 42
	v_readlane_b32 s7, v252, 43
	s_branch .LBB0_92

.LBB0_92:
	v_lshrrev_b32_e32 v0, 2, v209
	s_movk_i32 s2, 0x80
	v_cmp_gt_i32_e32 vcc, s2, v209
	v_subrev_u32_e32 v2, 0x60, v209
	s_nop 0
	v_cndmask_b32_e32 v0, v2, v0, vcc
	s_movk_i32 s2, 0x7f
	v_lshlrev_b32_e32 v5, 2, v0
	v_or_b32_e32 v0, v5, v133
	v_cmp_lt_i32_e64 s[44:45], s2, v0
	s_movk_i32 s2, 0x80
	v_cmp_gt_i32_e32 vcc, s2, v0
	s_and_saveexec_b64 s[2:3], vcc
	s_xor_b64 s[2:3], exec, s[2:3]
	v_ashrrev_i32_e32 v4, 1, v0
	s_or_saveexec_b64 s[2:3], s[2:3]
	v_mov_b32_e32 v176, 0
	v_mov_b32_e32 v3, 0x1000
	v_mov_b32_e32 v2, 0
	s_xor_b64 exec, exec, s[2:3]
	v_add_u32_e32 v2, 0xffffff80, v5
	v_bfe_u32 v4, v0, 1, 6
	v_lshrrev_b32_e32 v0, 6, v2
	v_and_b32_e32 v2, 0x3fffffe, v0
	v_mov_b32_e32 v3, 0x100
	s_or_b64 exec, exec, s[2:3]
	v_add_u32_e32 v6, v4, v206
	v_ashrrev_i32_e32 v7, 31, v6
	v_lshlrev_b64 v[6:7], 12, v[6:7]
	v_lshl_add_u64 v[8:9], v[142:143], 0, v[6:7]
	v_lshl_add_u64 v[6:7], v[144:145], 0, v[6:7]
	global_load_dwordx4 v[66:69], v[8:9], off
	global_load_dwordx4 v[70:73], v[8:9], off offset:1024
	global_load_dwordx4 v[74:77], v[8:9], off offset:2048
	global_load_dwordx4 v[78:81], v[8:9], off offset:3072
	global_load_dwordx4 v[82:85], v[6:7], off
	global_load_dwordx4 v[86:89], v[6:7], off offset:64
	global_load_dwordx4 v[90:93], v[6:7], off offset:128
	global_load_dwordx4 v[94:97], v[6:7], off offset:192
	v_lshlrev_b32_e32 v6, 6, v4
	v_ashrrev_i32_e32 v7, 31, v6
	v_readlane_b32 s4, v253, 33
	v_lshl_add_u64 v[8:9], v[136:137], 0, v[6:7]
	v_readlane_b32 s14, v253, 43
	v_readlane_b32 s15, v253, 44
	v_or_b32_e32 v0, v2, v141
	v_lshlrev_b32_e32 v0, 1, v0
	v_lshl_add_u64 v[8:9], v[8:9], 3, s[14:15]
	global_load_dwordx2 v[152:153], v[8:9], off
	global_load_dwordx2 v[154:155], v[8:9], off offset:256
	v_lshl_add_u64 v[8:9], v[0:1], 0, s[0:1]
	v_lshlrev_b64 v[8:9], 14, v[8:9]
	v_lshl_add_u64 v[6:7], v[138:139], 0, v[6:7]
	v_lshl_add_u64 v[150:151], v[6:7], 0, v[8:9]
	v_mov_b32_e32 v180, 0
	v_mov_b32_e32 v178, 0
	v_mov_b32_e32 v182, 0
	v_readlane_b32 s5, v253, 34
	v_readlane_b32 s6, v253, 35
	v_readlane_b32 s7, v253, 36
	v_readlane_b32 s8, v253, 37
	v_readlane_b32 s9, v253, 38
	v_readlane_b32 s10, v253, 39
	v_readlane_b32 s11, v253, 40
	v_readlane_b32 s12, v253, 41
	v_readlane_b32 s13, v253, 42
	v_readlane_b32 s16, v253, 45
	v_readlane_b32 s17, v253, 46
	v_readlane_b32 s18, v253, 47
	v_readlane_b32 s19, v253, 48
	s_and_saveexec_b64 s[2:3], vcc
	s_cbranch_execz .LBB0_98
	v_readlane_b32 s4, v253, 49
	v_readlane_b32 s14, v253, 59
	v_readlane_b32 s15, v253, 60
	v_readlane_b32 s5, v253, 50
	v_readlane_b32 s6, v253, 51
	v_lshl_add_u64 v[6:7], v[150:151], 2, s[14:15]
	v_add_co_u32_e32 v8, vcc, 0x4000, v6
	v_readlane_b32 s7, v253, 52
	s_nop 0
	v_addc_co_u32_e32 v9, vcc, 0, v7, vcc
	global_load_dword v182, v[6:7], off
	global_load_dword v178, v[8:9], off
	global_load_dword v176, v[8:9], off offset:128
	global_load_dword v180, v[6:7], off offset:128
	v_readlane_b32 s8, v253, 53
	v_readlane_b32 s9, v253, 54
	v_readlane_b32 s10, v253, 55
	v_readlane_b32 s11, v253, 56
	v_readlane_b32 s12, v253, 57
	v_readlane_b32 s13, v253, 58
	v_readlane_b32 s16, v253, 61
	v_readlane_b32 s17, v253, 62
	v_readlane_b32 s18, v253, 63
	v_readlane_b32 s19, v254, 0

.LBB0_100:
	s_waitcnt vmcnt(0)
	v_readfirstlane_b32 s52, v149
	s_mov_b32 s50, 0x10000
	s_mov_b32 s51, 0
	s_mov_b32 s54, 0x1000
	s_mov_b32 s55, 0
	s_mov_b32 s56, 0x3000
	s_mov_b32 s57, 0
	v_add_u32_e32 v0, 32, v210
	v_cndmask_b32_e64 v0, v0, 0, s[40:41]
	v_and_or_b32 v12, v203, 15, v0
	v_ashrrev_i32_e32 v13, 31, v12
	v_cvt_pk_bf16_f32 v212, v8, v9
	v_cvt_pk_bf16_f32 v213, v10, v11
	v_cvt_pk_bf16_f32 v214, v4, v5
	v_cvt_pk_bf16_f32 v215, v6, v7
	v_and_b32_e32 v16, 48, v203
	v_and_b32_e32 v17, 15, v203
	v_lshlrev_b32_e32 v17, 2, v17
	v_sub_u32_e32 v16, v16, v17
	v_ashrrev_i32_e32 v17, 31, v16
	v_lshl_add_u64 v[14:15], v[12:13], 0, v[164:165]
	v_lshlrev_b64 v[14:15], 12, v[14:15]
	v_lshl_add_u64 v[14:15], v[162:163], 0, v[14:15]
	v_lshl_add_u64 v[240:241], v[14:15], 0, v[16:17]
	v_lshl_add_u64 v[14:15], v[12:13], 0, v[166:167]
	v_lshlrev_b64 v[14:15], 12, v[14:15]
	v_lshl_add_u64 v[14:15], v[162:163], 0, v[14:15]
	v_lshl_add_u64 v[244:245], v[14:15], 0, v[16:17]
	s_cmp_lg_u64 s[40:41], 0
	s_cbranch_scc1 .LS5Q_dsel
	s_mov_b32 s50, 0xffff0000
	s_mov_b32 s51, -1
.LS5Q_dsel:
	v_readfirstlane_b32 s60, v209
	v_readfirstlane_b32 s61, v134
	s_cmpk_lt_u32 s60, 0x80
	s_cbranch_scc1 .LS5Q_pair
	v_mfma_f32_32x32x16_bf16 v[34:49], v[212:215], v[66:69], 0
	v_mfma_f32_32x32x16_bf16 v[50:65], v[212:215], v[74:77], 0
	s_nop 7
	s_cmp_lg_u64 s[40:41], 0
	s_cbranch_scc1 .LS5P_loopd0

.LS5P_epi:
	ds_read_b128 v[216:219], v208
	ds_read_b128 v[220:223], v208 offset:4352
	ds_read_b128 v[224:227], v208 offset:64
	ds_read_b128 v[228:231], v208 offset:4416
	ds_read_b128 v[2:5], v208 offset:128
	ds_read_b128 v[6:9], v208 offset:4480
	ds_read_b128 v[10:13], v208 offset:192
	ds_read_b128 v[14:17], v208 offset:4544
	s_waitcnt lgkmcnt(6)
	v_mfma_f32_16x16x32_bf16 v[232:235], v[82:85], v[216:219], 0
	v_mfma_f32_16x16x32_bf16 v[236:239], v[82:85], v[220:223], 0
	s_waitcnt lgkmcnt(4)
	v_mfma_f32_16x16x32_bf16 v[232:235], v[86:89], v[224:227], v[232:235]
	v_mfma_f32_16x16x32_bf16 v[236:239], v[86:89], v[228:231], v[236:239]
	s_waitcnt lgkmcnt(2)
	v_mfma_f32_16x16x32_bf16 v[232:235], v[90:93], v[2:5], v[232:235]
	v_mfma_f32_16x16x32_bf16 v[236:239], v[90:93], v[6:9], v[236:239]
	s_waitcnt lgkmcnt(0)
	v_mfma_f32_16x16x32_bf16 v[232:235], v[94:97], v[10:13], v[232:235]
	v_mfma_f32_16x16x32_bf16 v[236:239], v[94:97], v[14:17], v[236:239]
	s_nop 7
	global_store_dwordx4 v[240:241], v[232:235], off
	global_store_dwordx4 v[244:245], v[236:239], off
	s_branch .LS5Q_done
.LS5Q_pair:
	s_bitcmp1_b32 s61, 6
	s_cbranch_scc1 .LS5Q_roleB
	v_mov_b32_e32 v172, v207
	v_mov_b32_e32 v173, v208
	v_mfma_f32_32x32x16_bf16 v[34:49], v[212:215], v[66:69], 0
	v_mfma_f32_32x32x16_bf16 v[50:65], v[212:215], v[74:77], 0
	s_branch .LS5Q_common
.LS5Q_roleB:
	v_add_u32_e32 v172, 0x80, v207
	v_add_u32_e32 v173, 0x1100, v208
	v_mov_b64_e32 v[240:241], v[244:245]
	v_mfma_f32_32x32x16_bf16 v[34:49], v[212:215], v[70:73], 0
	v_mfma_f32_32x32x16_bf16 v[50:65], v[212:215], v[78:81], 0
.LS5Q_common:
	v_lshl_add_u64 v[248:249], v[248:249], 0, s[50:51]
	global_load_dwordx4 v[110:113], v[248:249], off offset:16
	global_load_dwordx4 v[106:109], v[248:249], off
	s_nop 7
	s_bitcmp1_b32 s61, 6
	s_cbranch_scc1 .LS5Q_selB
	s_cmp_lg_u64 s[40:41], 0
	s_cbranch_scc1 .LS5Q_loopr0d0
	s_branch .LS5Q_loopr0d1
.LS5Q_selB:
	s_cmp_lg_u64 s[40:41], 0
	s_cbranch_scc1 .LS5Q_loopr1d0
.LS5Q_loopr1d1:
	s_cmp_lt_u32 s28, 3
	s_cbranch_scc0 .LS5Q_wr1d1e
	s_waitcnt vmcnt(2)
.LS5Q_wr1d1e:
	s_waitcnt vmcnt(4)
	v_cvt_pk_bf16_f32 v212, v102, v103
	v_cvt_pk_bf16_f32 v213, v104, v105
	v_cvt_pk_bf16_f32 v214, v98, v99
	v_cvt_pk_bf16_f32 v215, v100, v101
	s_add_u32 s20, s28, 3
	s_cmp_lt_u32 s20, s52
	s_cselect_b64 s[58:59], s[50:51], 0
	v_lshl_add_u64 v[248:249], v[248:249], 0, s[58:59]
	global_load_dwordx4 v[98:101], v[248:249], off offset:16
	global_load_dwordx4 v[102:105], v[248:249], off
	ds_read_b128 v[216:219], v173 offset:60416
	ds_read_b128 v[220:223], v173 offset:60480
	ds_read_b128 v[224:227], v173 offset:60544
	ds_read_b128 v[228:231], v173 offset:60608
	v_fmac_f32_e32 v49, v154, v180
	v_fmac_f32_e32 v65, v154, v176
	v_fma_f32 v49, -v155, v176, v49
	v_fmac_f32_e32 v65, v155, v180
	v_mfma_f32_32x32x16_bf16 v[2:17], v[212:215], v[70:73], 0
	v_fmac_f32_e32 v48, v154, v49
	v_fmac_f32_e32 v64, v154, v65
	v_cvt_pk_bf16_f32 v184, v49, v65
	v_fma_f32 v48, -v155, v65, v48
	v_fmac_f32_e32 v64, v155, v49
	ds_write_b32 v172, v184 offset:4080
	v_fmac_f32_e32 v47, v154, v48
	v_fmac_f32_e32 v63, v154, v64
	v_cvt_pk_bf16_f32 v185, v48, v64
	v_fma_f32 v47, -v155, v64, v47
	v_fmac_f32_e32 v63, v155, v48
	ds_write_b32 v172, v185 offset:3808
	v_mfma_f32_32x32x16_bf16 v[18:33], v[212:215], v[78:81], 0
	v_fmac_f32_e32 v46, v154, v47
	v_fmac_f32_e32 v62, v154, v63
	v_cvt_pk_bf16_f32 v184, v47, v63
	v_fma_f32 v46, -v155, v63, v46
	v_fmac_f32_e32 v62, v155, v47
	ds_write_b32 v172, v184 offset:3536
	v_fmac_f32_e32 v45, v154, v46
	v_fmac_f32_e32 v61, v154, v62
	v_cvt_pk_bf16_f32 v185, v46, v62
	v_fma_f32 v45, -v155, v62, v45
	v_fmac_f32_e32 v61, v155, v46
	ds_write_b32 v172, v185 offset:3264
	s_waitcnt lgkmcnt(4)
	v_mfma_f32_16x16x32_bf16 v[232:235], v[82:85], v[216:219], 0
	v_fmac_f32_e32 v44, v154, v45
	v_fmac_f32_e32 v60, v154, v61
	v_cvt_pk_bf16_f32 v184, v45, v61
	v_fma_f32 v44, -v155, v61, v44
	v_fmac_f32_e32 v60, v155, v45
	ds_write_b32 v172, v184 offset:2992
	v_mfma_f32_16x16x32_bf16 v[232:235], v[86:89], v[220:223], v[232:235]
	v_fmac_f32_e32 v43, v154, v44
	v_fmac_f32_e32 v59, v154, v60
	v_cvt_pk_bf16_f32 v185, v44, v60
	v_fma_f32 v43, -v155, v60, v43
	v_fmac_f32_e32 v59, v155, v44
	ds_write_b32 v172, v185 offset:2720
	v_mfma_f32_16x16x32_bf16 v[232:235], v[90:93], v[224:227], v[232:235]
	v_fmac_f32_e32 v42, v154, v43
	v_fmac_f32_e32 v58, v154, v59
	v_cvt_pk_bf16_f32 v184, v43, v59
	v_fma_f32 v42, -v155, v59, v42
	v_fmac_f32_e32 v58, v155, v43
	ds_write_b32 v172, v184 offset:2448
	v_mfma_f32_16x16x32_bf16 v[232:235], v[94:97], v[228:231], v[232:235]
	v_fmac_f32_e32 v41, v154, v42
	v_fmac_f32_e32 v57, v154, v58
	v_cvt_pk_bf16_f32 v185, v42, v58
	v_fma_f32 v41, -v155, v58, v41
	v_fmac_f32_e32 v57, v155, v42
	ds_write_b32 v172, v185 offset:2176
	v_fmac_f32_e32 v40, v154, v41
	v_fmac_f32_e32 v56, v154, v57
	v_cvt_pk_bf16_f32 v184, v41, v57
	v_fma_f32 v40, -v155, v57, v40
	v_fmac_f32_e32 v56, v155, v41
	ds_write_b32 v172, v184 offset:1904
	v_fmac_f32_e32 v39, v154, v40
	v_fmac_f32_e32 v55, v154, v56
	v_cvt_pk_bf16_f32 v185, v40, v56
	v_fma_f32 v39, -v155, v56, v39
	v_fmac_f32_e32 v55, v155, v40
	ds_write_b32 v172, v185 offset:1632
	s_cmp_eq_u32 s28, 0
	s_cbranch_scc1 .LS5Q_nstr1d1e
	global_store_dwordx4 v[240:241], v[232:235], off
	v_lshl_add_u64 v[240:241], v[240:241], 0, s[50:51]
.LS5Q_nstr1d1e:
	v_fmac_f32_e32 v38, v154, v39
	v_fmac_f32_e32 v54, v154, v55
	v_cvt_pk_bf16_f32 v184, v39, v55
	v_fma_f32 v38, -v155, v55, v38
	v_fmac_f32_e32 v54, v155, v39
	ds_write_b32 v172, v184 offset:1360
	v_fmac_f32_e32 v37, v154, v38
	v_fmac_f32_e32 v53, v154, v54
	v_cvt_pk_bf16_f32 v185, v38, v54
	v_fma_f32 v37, -v155, v54, v37
	v_fmac_f32_e32 v53, v155, v38
	ds_write_b32 v172, v185 offset:1088
	v_fmac_f32_e32 v36, v154, v37
	v_fmac_f32_e32 v52, v154, v53
	v_cvt_pk_bf16_f32 v184, v37, v53
	v_fma_f32 v36, -v155, v53, v36
	v_fmac_f32_e32 v52, v155, v37
	ds_write_b32 v172, v184 offset:816
	v_fmac_f32_e32 v35, v154, v36
	v_fmac_f32_e32 v51, v154, v52
	v_cvt_pk_bf16_f32 v185, v36, v52
	v_fma_f32 v35, -v155, v52, v35
	v_fmac_f32_e32 v51, v155, v36
	ds_write_b32 v172, v185 offset:544
	v_fma_f32 v180, v154, v35, v34
	v_fma_f32 v176, v154, v51, v50
	v_cvt_pk_bf16_f32 v184, v35, v51
	v_fma_f32 v180, -v155, v51, v180
	v_fmac_f32_e32 v176, v155, v35
	ds_write_b32 v172, v184 offset:272
	v_cvt_pk_bf16_f32 v185, v180, v176
	ds_write_b32 v172, v185 offset:0
	s_waitcnt lgkmcnt(0)
	s_barrier
	s_add_u32 s28, s28, 1
	s_cmp_lt_u32 s28, 3
	s_cbranch_scc0 .LS5Q_wr1d1o
	s_waitcnt vmcnt(2)
.LS5Q_wr1d1o:
	s_waitcnt vmcnt(4)
	v_cvt_pk_bf16_f32 v212, v106, v107
	v_cvt_pk_bf16_f32 v213, v108, v109
	v_cvt_pk_bf16_f32 v214, v110, v111
	v_cvt_pk_bf16_f32 v215, v112, v113
	s_add_u32 s20, s28, 3
	s_cmp_lt_u32 s20, s52
	s_cselect_b64 s[58:59], s[50:51], 0
	v_lshl_add_u64 v[248:249], v[248:249], 0, s[58:59]
	global_load_dwordx4 v[110:113], v[248:249], off offset:16
	global_load_dwordx4 v[106:109], v[248:249], off
	ds_read_b128 v[216:219], v173 offset:0
	ds_read_b128 v[220:223], v173 offset:64
	ds_read_b128 v[224:227], v173 offset:128
	ds_read_b128 v[228:231], v173 offset:192
	v_fmac_f32_e32 v17, v154, v180
	v_fmac_f32_e32 v33, v154, v176
	v_fma_f32 v17, -v155, v176, v17
	v_fmac_f32_e32 v33, v155, v180
	v_mfma_f32_32x32x16_bf16 v[34:49], v[212:215], v[70:73], 0
	v_fmac_f32_e32 v16, v154, v17
	v_fmac_f32_e32 v32, v154, v33
	v_cvt_pk_bf16_f32 v184, v17, v33
	v_fma_f32 v16, -v155, v33, v16
	v_fmac_f32_e32 v32, v155, v17
	ds_write_b32 v172, v184 offset:64496
	v_fmac_f32_e32 v15, v154, v16
	v_fmac_f32_e32 v31, v154, v32
	v_cvt_pk_bf16_f32 v185, v16, v32
	v_fma_f32 v15, -v155, v32, v15
	v_fmac_f32_e32 v31, v155, v16
	ds_write_b32 v172, v185 offset:64224
	v_mfma_f32_32x32x16_bf16 v[50:65], v[212:215], v[78:81], 0
	v_fmac_f32_e32 v14, v154, v15
	v_fmac_f32_e32 v30, v154, v31
	v_cvt_pk_bf16_f32 v184, v15, v31
	v_fma_f32 v14, -v155, v31, v14
	v_fmac_f32_e32 v30, v155, v15
	ds_write_b32 v172, v184 offset:63952
	v_fmac_f32_e32 v13, v154, v14
	v_fmac_f32_e32 v29, v154, v30
	v_cvt_pk_bf16_f32 v185, v14, v30
	v_fma_f32 v13, -v155, v30, v13
	v_fmac_f32_e32 v29, v155, v14
	ds_write_b32 v172, v185 offset:63680
	s_waitcnt lgkmcnt(4)
	v_mfma_f32_16x16x32_bf16 v[232:235], v[82:85], v[216:219], 0
	v_fmac_f32_e32 v12, v154, v13
	v_fmac_f32_e32 v28, v154, v29
	v_cvt_pk_bf16_f32 v184, v13, v29
	v_fma_f32 v12, -v155, v29, v12
	v_fmac_f32_e32 v28, v155, v13
	ds_write_b32 v172, v184 offset:63408
	v_mfma_f32_16x16x32_bf16 v[232:235], v[86:89], v[220:223], v[232:235]
	v_fmac_f32_e32 v11, v154, v12
	v_fmac_f32_e32 v27, v154, v28
	v_cvt_pk_bf16_f32 v185, v12, v28
	v_fma_f32 v11, -v155, v28, v11
	v_fmac_f32_e32 v27, v155, v12
	ds_write_b32 v172, v185 offset:63136
	v_mfma_f32_16x16x32_bf16 v[232:235], v[90:93], v[224:227], v[232:235]
	v_fmac_f32_e32 v10, v154, v11
	v_fmac_f32_e32 v26, v154, v27
	v_cvt_pk_bf16_f32 v184, v11, v27
	v_fma_f32 v10, -v155, v27, v10
	v_fmac_f32_e32 v26, v155, v11
	ds_write_b32 v172, v184 offset:62864
	v_mfma_f32_16x16x32_bf16 v[232:235], v[94:97], v[228:231], v[232:235]
	v_fmac_f32_e32 v9, v154, v10
	v_fmac_f32_e32 v25, v154, v26
	v_cvt_pk_bf16_f32 v185, v10, v26
	v_fma_f32 v9, -v155, v26, v9
	v_fmac_f32_e32 v25, v155, v10
	ds_write_b32 v172, v185 offset:62592
	v_fmac_f32_e32 v8, v154, v9
	v_fmac_f32_e32 v24, v154, v25
	v_cvt_pk_bf16_f32 v184, v9, v25
	v_fma_f32 v8, -v155, v25, v8
	v_fmac_f32_e32 v24, v155, v9
	ds_write_b32 v172, v184 offset:62320
	v_fmac_f32_e32 v7, v154, v8
	v_fmac_f32_e32 v23, v154, v24
	v_cvt_pk_bf16_f32 v185, v8, v24
	v_fma_f32 v7, -v155, v24, v7
	v_fmac_f32_e32 v23, v155, v8
	ds_write_b32 v172, v185 offset:62048
	global_store_dwordx4 v[240:241], v[232:235], off
	v_lshl_add_u64 v[240:241], v[240:241], 0, s[50:51]
	v_fmac_f32_e32 v6, v154, v7
	v_fmac_f32_e32 v22, v154, v23
	v_cvt_pk_bf16_f32 v184, v7, v23
	v_fma_f32 v6, -v155, v23, v6
	v_fmac_f32_e32 v22, v155, v7
	ds_write_b32 v172, v184 offset:61776
	v_fmac_f32_e32 v5, v154, v6
	v_fmac_f32_e32 v21, v154, v22
	v_cvt_pk_bf16_f32 v185, v6, v22
	v_fma_f32 v5, -v155, v22, v5
	v_fmac_f32_e32 v21, v155, v6
	ds_write_b32 v172, v185 offset:61504
	v_fmac_f32_e32 v4, v154, v5
	v_fmac_f32_e32 v20, v154, v21
	v_cvt_pk_bf16_f32 v184, v5, v21
	v_fma_f32 v4, -v155, v21, v4
	v_fmac_f32_e32 v20, v155, v5
	ds_write_b32 v172, v184 offset:61232
	v_fmac_f32_e32 v3, v154, v4
	v_fmac_f32_e32 v19, v154, v20
	v_cvt_pk_bf16_f32 v185, v4, v20
	v_fma_f32 v3, -v155, v20, v3
	v_fmac_f32_e32 v19, v155, v4
	ds_write_b32 v172, v185 offset:60960
	v_fma_f32 v180, v154, v3, v2
	v_fma_f32 v176, v154, v19, v18
	v_cvt_pk_bf16_f32 v184, v3, v19
	v_fma_f32 v180, -v155, v19, v180
	v_fmac_f32_e32 v176, v155, v3
	ds_write_b32 v172, v184 offset:60688
	v_cvt_pk_bf16_f32 v185, v180, v176
	ds_write_b32 v172, v185 offset:60416
	s_waitcnt lgkmcnt(0)
	s_barrier
	s_add_u32 s28, s28, 1
	s_cmp_lt_u32 s28, s52
	s_cbranch_scc1 .LS5Q_loopr1d1
	s_branch .LS5Q_epi

.LS5Q_wr1d0e:
	s_waitcnt vmcnt(4)
	v_cvt_pk_bf16_f32 v212, v102, v103
	v_cvt_pk_bf16_f32 v213, v104, v105
	v_cvt_pk_bf16_f32 v214, v98, v99
	v_cvt_pk_bf16_f32 v215, v100, v101
	s_add_u32 s20, s28, 3
	s_cmp_lt_u32 s20, s52
	s_cselect_b64 s[58:59], s[50:51], 0
	v_lshl_add_u64 v[248:249], v[248:249], 0, s[58:59]
	global_load_dwordx4 v[98:101], v[248:249], off offset:16
	global_load_dwordx4 v[102:105], v[248:249], off
	ds_read_b128 v[216:219], v173 offset:60416
	ds_read_b128 v[220:223], v173 offset:60480
	ds_read_b128 v[224:227], v173 offset:60544
	ds_read_b128 v[228:231], v173 offset:60608
	v_fmac_f32_e32 v34, v154, v180
	v_fmac_f32_e32 v50, v154, v176
	v_fma_f32 v34, -v155, v176, v34
	v_fmac_f32_e32 v50, v155, v180
	v_mfma_f32_32x32x16_bf16 v[2:17], v[212:215], v[70:73], 0
	v_fmac_f32_e32 v35, v154, v34
	v_fmac_f32_e32 v51, v154, v50
	v_cvt_pk_bf16_f32 v184, v34, v50
	v_fma_f32 v35, -v155, v50, v35
	v_fmac_f32_e32 v51, v155, v34
	ds_write_b32 v172, v184 offset:0
	v_fmac_f32_e32 v36, v154, v35
	v_fmac_f32_e32 v52, v154, v51
	v_cvt_pk_bf16_f32 v185, v35, v51
	v_fma_f32 v36, -v155, v51, v36
	v_fmac_f32_e32 v52, v155, v35
	ds_write_b32 v172, v185 offset:272
	v_mfma_f32_32x32x16_bf16 v[18:33], v[212:215], v[78:81], 0
	v_fmac_f32_e32 v37, v154, v36
	v_fmac_f32_e32 v53, v154, v52
	v_cvt_pk_bf16_f32 v184, v36, v52
	v_fma_f32 v37, -v155, v52, v37
	v_fmac_f32_e32 v53, v155, v36
	ds_write_b32 v172, v184 offset:544
	v_fmac_f32_e32 v38, v154, v37
	v_fmac_f32_e32 v54, v154, v53
	v_cvt_pk_bf16_f32 v185, v37, v53
	v_fma_f32 v38, -v155, v53, v38
	v_fmac_f32_e32 v54, v155, v37
	ds_write_b32 v172, v185 offset:816
	s_waitcnt lgkmcnt(4)
	v_mfma_f32_16x16x32_bf16 v[232:235], v[82:85], v[216:219], 0
	v_fmac_f32_e32 v39, v154, v38
	v_fmac_f32_e32 v55, v154, v54
	v_cvt_pk_bf16_f32 v184, v38, v54
	v_fma_f32 v39, -v155, v54, v39
	v_fmac_f32_e32 v55, v155, v38
	ds_write_b32 v172, v184 offset:1088
	v_mfma_f32_16x16x32_bf16 v[232:235], v[86:89], v[220:223], v[232:235]
	v_fmac_f32_e32 v40, v154, v39
	v_fmac_f32_e32 v56, v154, v55
	v_cvt_pk_bf16_f32 v185, v39, v55
	v_fma_f32 v40, -v155, v55, v40
	v_fmac_f32_e32 v56, v155, v39
	ds_write_b32 v172, v185 offset:1360
	v_mfma_f32_16x16x32_bf16 v[232:235], v[90:93], v[224:227], v[232:235]
	v_fmac_f32_e32 v41, v154, v40
	v_fmac_f32_e32 v57, v154, v56
	v_cvt_pk_bf16_f32 v184, v40, v56
	v_fma_f32 v41, -v155, v56, v41
	v_fmac_f32_e32 v57, v155, v40
	ds_write_b32 v172, v184 offset:1632
	v_mfma_f32_16x16x32_bf16 v[232:235], v[94:97], v[228:231], v[232:235]
	v_fmac_f32_e32 v42, v154, v41
	v_fmac_f32_e32 v58, v154, v57
	v_cvt_pk_bf16_f32 v185, v41, v57
	v_fma_f32 v42, -v155, v57, v42
	v_fmac_f32_e32 v58, v155, v41
	ds_write_b32 v172, v185 offset:1904
	v_fmac_f32_e32 v43, v154, v42
	v_fmac_f32_e32 v59, v154, v58
	v_cvt_pk_bf16_f32 v184, v42, v58
	v_fma_f32 v43, -v155, v58, v43
	v_fmac_f32_e32 v59, v155, v42
	ds_write_b32 v172, v184 offset:2176
	v_fmac_f32_e32 v44, v154, v43
	v_fmac_f32_e32 v60, v154, v59
	v_cvt_pk_bf16_f32 v185, v43, v59
	v_fma_f32 v44, -v155, v59, v44
	v_fmac_f32_e32 v60, v155, v43
	ds_write_b32 v172, v185 offset:2448
	s_cmp_eq_u32 s28, 0
	s_cbranch_scc1 .LS5Q_nstr1d0e
	global_store_dwordx4 v[240:241], v[232:235], off
	v_lshl_add_u64 v[240:241], v[240:241], 0, s[50:51]
.LS5Q_nstr1d0e:
	v_fmac_f32_e32 v45, v154, v44
	v_fmac_f32_e32 v61, v154, v60
	v_cvt_pk_bf16_f32 v184, v44, v60
	v_fma_f32 v45, -v155, v60, v45
	v_fmac_f32_e32 v61, v155, v44
	ds_write_b32 v172, v184 offset:2720
	v_fmac_f32_e32 v46, v154, v45
	v_fmac_f32_e32 v62, v154, v61
	v_cvt_pk_bf16_f32 v185, v45, v61
	v_fma_f32 v46, -v155, v61, v46
	v_fmac_f32_e32 v62, v155, v45
	ds_write_b32 v172, v185 offset:2992
	v_fmac_f32_e32 v47, v154, v46
	v_fmac_f32_e32 v63, v154, v62
	v_cvt_pk_bf16_f32 v184, v46, v62
	v_fma_f32 v47, -v155, v62, v47
	v_fmac_f32_e32 v63, v155, v46
	ds_write_b32 v172, v184 offset:3264
	v_fmac_f32_e32 v48, v154, v47
	v_fmac_f32_e32 v64, v154, v63
	v_cvt_pk_bf16_f32 v185, v47, v63
	v_fma_f32 v48, -v155, v63, v48
	v_fmac_f32_e32 v64, v155, v47
	ds_write_b32 v172, v185 offset:3536
	v_fma_f32 v180, v154, v48, v49
	v_fma_f32 v176, v154, v64, v65
	v_cvt_pk_bf16_f32 v184, v48, v64
	v_fma_f32 v180, -v155, v64, v180
	v_fmac_f32_e32 v176, v155, v48
	ds_write_b32 v172, v184 offset:3808
	v_cvt_pk_bf16_f32 v185, v180, v176
	ds_write_b32 v172, v185 offset:4080
	s_waitcnt lgkmcnt(0)
	s_barrier
	s_add_u32 s28, s28, 1
	s_cmp_lt_u32 s28, 3
	s_cbranch_scc0 .LS5Q_wr1d0o
	s_waitcnt vmcnt(2)
.LS5Q_wr1d0o:
	s_waitcnt vmcnt(4)
	v_cvt_pk_bf16_f32 v212, v106, v107
	v_cvt_pk_bf16_f32 v213, v108, v109
	v_cvt_pk_bf16_f32 v214, v110, v111
	v_cvt_pk_bf16_f32 v215, v112, v113
	s_add_u32 s20, s28, 3
	s_cmp_lt_u32 s20, s52
	s_cselect_b64 s[58:59], s[50:51], 0
	v_lshl_add_u64 v[248:249], v[248:249], 0, s[58:59]
	global_load_dwordx4 v[110:113], v[248:249], off offset:16
	global_load_dwordx4 v[106:109], v[248:249], off
	ds_read_b128 v[216:219], v173 offset:0
	ds_read_b128 v[220:223], v173 offset:64
	ds_read_b128 v[224:227], v173 offset:128
	ds_read_b128 v[228:231], v173 offset:192
	v_fmac_f32_e32 v2, v154, v180
	v_fmac_f32_e32 v18, v154, v176
	v_fma_f32 v2, -v155, v176, v2
	v_fmac_f32_e32 v18, v155, v180
	v_mfma_f32_32x32x16_bf16 v[34:49], v[212:215], v[70:73], 0
	v_fmac_f32_e32 v3, v154, v2
	v_fmac_f32_e32 v19, v154, v18
	v_cvt_pk_bf16_f32 v184, v2, v18
	v_fma_f32 v3, -v155, v18, v3
	v_fmac_f32_e32 v19, v155, v2
	ds_write_b32 v172, v184 offset:60416
	v_fmac_f32_e32 v4, v154, v3
	v_fmac_f32_e32 v20, v154, v19
	v_cvt_pk_bf16_f32 v185, v3, v19
	v_fma_f32 v4, -v155, v19, v4
	v_fmac_f32_e32 v20, v155, v3
	ds_write_b32 v172, v185 offset:60688
	v_mfma_f32_32x32x16_bf16 v[50:65], v[212:215], v[78:81], 0
	v_fmac_f32_e32 v5, v154, v4
	v_fmac_f32_e32 v21, v154, v20
	v_cvt_pk_bf16_f32 v184, v4, v20
	v_fma_f32 v5, -v155, v20, v5
	v_fmac_f32_e32 v21, v155, v4
	ds_write_b32 v172, v184 offset:60960
	v_fmac_f32_e32 v6, v154, v5
	v_fmac_f32_e32 v22, v154, v21
	v_cvt_pk_bf16_f32 v185, v5, v21
	v_fma_f32 v6, -v155, v21, v6
	v_fmac_f32_e32 v22, v155, v5
	ds_write_b32 v172, v185 offset:61232
	s_waitcnt lgkmcnt(4)
	v_mfma_f32_16x16x32_bf16 v[232:235], v[82:85], v[216:219], 0
	v_fmac_f32_e32 v7, v154, v6
	v_fmac_f32_e32 v23, v154, v22
	v_cvt_pk_bf16_f32 v184, v6, v22
	v_fma_f32 v7, -v155, v22, v7
	v_fmac_f32_e32 v23, v155, v6
	ds_write_b32 v172, v184 offset:61504
	v_mfma_f32_16x16x32_bf16 v[232:235], v[86:89], v[220:223], v[232:235]
	v_fmac_f32_e32 v8, v154, v7
	v_fmac_f32_e32 v24, v154, v23
	v_cvt_pk_bf16_f32 v185, v7, v23
	v_fma_f32 v8, -v155, v23, v8
	v_fmac_f32_e32 v24, v155, v7
	ds_write_b32 v172, v185 offset:61776
	v_mfma_f32_16x16x32_bf16 v[232:235], v[90:93], v[224:227], v[232:235]
	v_fmac_f32_e32 v9, v154, v8
	v_fmac_f32_e32 v25, v154, v24
	v_cvt_pk_bf16_f32 v184, v8, v24
	v_fma_f32 v9, -v155, v24, v9
	v_fmac_f32_e32 v25, v155, v8
	ds_write_b32 v172, v184 offset:62048
	v_mfma_f32_16x16x32_bf16 v[232:235], v[94:97], v[228:231], v[232:235]
	v_fmac_f32_e32 v10, v154, v9
	v_fmac_f32_e32 v26, v154, v25
	v_cvt_pk_bf16_f32 v185, v9, v25
	v_fma_f32 v10, -v155, v25, v10
	v_fmac_f32_e32 v26, v155, v9
	ds_write_b32 v172, v185 offset:62320
	v_fmac_f32_e32 v11, v154, v10
	v_fmac_f32_e32 v27, v154, v26
	v_cvt_pk_bf16_f32 v184, v10, v26
	v_fma_f32 v11, -v155, v26, v11
	v_fmac_f32_e32 v27, v155, v10
	ds_write_b32 v172, v184 offset:62592
	v_fmac_f32_e32 v12, v154, v11
	v_fmac_f32_e32 v28, v154, v27
	v_cvt_pk_bf16_f32 v185, v11, v27
	v_fma_f32 v12, -v155, v27, v12
	v_fmac_f32_e32 v28, v155, v11
	ds_write_b32 v172, v185 offset:62864
	global_store_dwordx4 v[240:241], v[232:235], off
	v_lshl_add_u64 v[240:241], v[240:241], 0, s[50:51]
	v_fmac_f32_e32 v13, v154, v12
	v_fmac_f32_e32 v29, v154, v28
	v_cvt_pk_bf16_f32 v184, v12, v28
	v_fma_f32 v13, -v155, v28, v13
	v_fmac_f32_e32 v29, v155, v12
	ds_write_b32 v172, v184 offset:63136
	v_fmac_f32_e32 v14, v154, v13
	v_fmac_f32_e32 v30, v154, v29
	v_cvt_pk_bf16_f32 v185, v13, v29
	v_fma_f32 v14, -v155, v29, v14
	v_fmac_f32_e32 v30, v155, v13
	ds_write_b32 v172, v185 offset:63408
	v_fmac_f32_e32 v15, v154, v14
	v_fmac_f32_e32 v31, v154, v30
	v_cvt_pk_bf16_f32 v184, v14, v30
	v_fma_f32 v15, -v155, v30, v15
	v_fmac_f32_e32 v31, v155, v14
	ds_write_b32 v172, v184 offset:63680
	v_fmac_f32_e32 v16, v154, v15
	v_fmac_f32_e32 v32, v154, v31
	v_cvt_pk_bf16_f32 v185, v15, v31
	v_fma_f32 v16, -v155, v31, v16
	v_fmac_f32_e32 v32, v155, v15
	ds_write_b32 v172, v185 offset:63952
	v_fma_f32 v180, v154, v16, v17
	v_fma_f32 v176, v154, v32, v33
	v_cvt_pk_bf16_f32 v184, v16, v32
	v_fma_f32 v180, -v155, v32, v180
	v_fmac_f32_e32 v176, v155, v16
	ds_write_b32 v172, v184 offset:64224
	v_cvt_pk_bf16_f32 v185, v180, v176
	ds_write_b32 v172, v185 offset:64496
	s_waitcnt lgkmcnt(0)
	s_barrier
	s_add_u32 s28, s28, 1
	s_cmp_lt_u32 s28, s52
	s_cbranch_scc1 .LS5Q_loopr1d0
	s_branch .LS5Q_epi

.LS5Q_wr0d1e:
	s_waitcnt vmcnt(4)
	v_cvt_pk_bf16_f32 v212, v102, v103
	v_cvt_pk_bf16_f32 v213, v104, v105
	v_cvt_pk_bf16_f32 v214, v98, v99
	v_cvt_pk_bf16_f32 v215, v100, v101
	s_add_u32 s20, s28, 3
	s_cmp_lt_u32 s20, s52
	s_cselect_b64 s[58:59], s[50:51], 0
	v_lshl_add_u64 v[248:249], v[248:249], 0, s[58:59]
	global_load_dwordx4 v[98:101], v[248:249], off offset:16
	global_load_dwordx4 v[102:105], v[248:249], off
	ds_read_b128 v[216:219], v173 offset:60416
	ds_read_b128 v[220:223], v173 offset:60480
	ds_read_b128 v[224:227], v173 offset:60544
	ds_read_b128 v[228:231], v173 offset:60608
	v_fmac_f32_e32 v49, v152, v182
	v_fmac_f32_e32 v65, v152, v178
	v_fma_f32 v49, -v153, v178, v49
	v_fmac_f32_e32 v65, v153, v182
	v_mfma_f32_32x32x16_bf16 v[2:17], v[212:215], v[66:69], 0
	v_fmac_f32_e32 v48, v152, v49
	v_fmac_f32_e32 v64, v152, v65
	v_cvt_pk_bf16_f32 v184, v49, v65
	v_fma_f32 v48, -v153, v65, v48
	v_fmac_f32_e32 v64, v153, v49
	ds_write_b32 v172, v184 offset:4080
	v_fmac_f32_e32 v47, v152, v48
	v_fmac_f32_e32 v63, v152, v64
	v_cvt_pk_bf16_f32 v185, v48, v64
	v_fma_f32 v47, -v153, v64, v47
	v_fmac_f32_e32 v63, v153, v48
	ds_write_b32 v172, v185 offset:3808
	v_mfma_f32_32x32x16_bf16 v[18:33], v[212:215], v[74:77], 0
	v_fmac_f32_e32 v46, v152, v47
	v_fmac_f32_e32 v62, v152, v63
	v_cvt_pk_bf16_f32 v184, v47, v63
	v_fma_f32 v46, -v153, v63, v46
	v_fmac_f32_e32 v62, v153, v47
	ds_write_b32 v172, v184 offset:3536
	v_fmac_f32_e32 v45, v152, v46
	v_fmac_f32_e32 v61, v152, v62
	v_cvt_pk_bf16_f32 v185, v46, v62
	v_fma_f32 v45, -v153, v62, v45
	v_fmac_f32_e32 v61, v153, v46
	ds_write_b32 v172, v185 offset:3264
	s_waitcnt lgkmcnt(4)
	v_mfma_f32_16x16x32_bf16 v[232:235], v[82:85], v[216:219], 0
	v_fmac_f32_e32 v44, v152, v45
	v_fmac_f32_e32 v60, v152, v61
	v_cvt_pk_bf16_f32 v184, v45, v61
	v_fma_f32 v44, -v153, v61, v44
	v_fmac_f32_e32 v60, v153, v45
	ds_write_b32 v172, v184 offset:2992
	v_mfma_f32_16x16x32_bf16 v[232:235], v[86:89], v[220:223], v[232:235]
	v_fmac_f32_e32 v43, v152, v44
	v_fmac_f32_e32 v59, v152, v60
	v_cvt_pk_bf16_f32 v185, v44, v60
	v_fma_f32 v43, -v153, v60, v43
	v_fmac_f32_e32 v59, v153, v44
	ds_write_b32 v172, v185 offset:2720
	v_mfma_f32_16x16x32_bf16 v[232:235], v[90:93], v[224:227], v[232:235]
	v_fmac_f32_e32 v42, v152, v43
	v_fmac_f32_e32 v58, v152, v59
	v_cvt_pk_bf16_f32 v184, v43, v59
	v_fma_f32 v42, -v153, v59, v42
	v_fmac_f32_e32 v58, v153, v43
	ds_write_b32 v172, v184 offset:2448
	v_mfma_f32_16x16x32_bf16 v[232:235], v[94:97], v[228:231], v[232:235]
	v_fmac_f32_e32 v41, v152, v42
	v_fmac_f32_e32 v57, v152, v58
	v_cvt_pk_bf16_f32 v185, v42, v58
	v_fma_f32 v41, -v153, v58, v41
	v_fmac_f32_e32 v57, v153, v42
	ds_write_b32 v172, v185 offset:2176
	v_fmac_f32_e32 v40, v152, v41
	v_fmac_f32_e32 v56, v152, v57
	v_cvt_pk_bf16_f32 v184, v41, v57
	v_fma_f32 v40, -v153, v57, v40
	v_fmac_f32_e32 v56, v153, v41
	ds_write_b32 v172, v184 offset:1904
	v_fmac_f32_e32 v39, v152, v40
	v_fmac_f32_e32 v55, v152, v56
	v_cvt_pk_bf16_f32 v185, v40, v56
	v_fma_f32 v39, -v153, v56, v39
	v_fmac_f32_e32 v55, v153, v40
	ds_write_b32 v172, v185 offset:1632
	s_cmp_eq_u32 s28, 0
	s_cbranch_scc1 .LS5Q_nstr0d1e
	global_store_dwordx4 v[240:241], v[232:235], off
	v_lshl_add_u64 v[240:241], v[240:241], 0, s[50:51]
.LS5Q_nstr0d1e:
	v_fmac_f32_e32 v38, v152, v39
	v_fmac_f32_e32 v54, v152, v55
	v_cvt_pk_bf16_f32 v184, v39, v55
	v_fma_f32 v38, -v153, v55, v38
	v_fmac_f32_e32 v54, v153, v39
	ds_write_b32 v172, v184 offset:1360
	v_fmac_f32_e32 v37, v152, v38
	v_fmac_f32_e32 v53, v152, v54
	v_cvt_pk_bf16_f32 v185, v38, v54
	v_fma_f32 v37, -v153, v54, v37
	v_fmac_f32_e32 v53, v153, v38
	ds_write_b32 v172, v185 offset:1088
	v_fmac_f32_e32 v36, v152, v37
	v_fmac_f32_e32 v52, v152, v53
	v_cvt_pk_bf16_f32 v184, v37, v53
	v_fma_f32 v36, -v153, v53, v36
	v_fmac_f32_e32 v52, v153, v37
	ds_write_b32 v172, v184 offset:816
	v_fmac_f32_e32 v35, v152, v36
	v_fmac_f32_e32 v51, v152, v52
	v_cvt_pk_bf16_f32 v185, v36, v52
	v_fma_f32 v35, -v153, v52, v35
	v_fmac_f32_e32 v51, v153, v36
	ds_write_b32 v172, v185 offset:544
	v_fma_f32 v182, v152, v35, v34
	v_fma_f32 v178, v152, v51, v50
	v_cvt_pk_bf16_f32 v184, v35, v51
	v_fma_f32 v182, -v153, v51, v182
	v_fmac_f32_e32 v178, v153, v35
	ds_write_b32 v172, v184 offset:272
	v_cvt_pk_bf16_f32 v185, v182, v178
	ds_write_b32 v172, v185 offset:0
	s_waitcnt lgkmcnt(0)
	s_barrier
	s_add_u32 s28, s28, 1
	s_cmp_lt_u32 s28, 3
	s_cbranch_scc0 .LS5Q_wr0d1o
	s_waitcnt vmcnt(2)
.LS5Q_wr0d1o:
	s_waitcnt vmcnt(4)
	v_cvt_pk_bf16_f32 v212, v106, v107
	v_cvt_pk_bf16_f32 v213, v108, v109
	v_cvt_pk_bf16_f32 v214, v110, v111
	v_cvt_pk_bf16_f32 v215, v112, v113
	s_add_u32 s20, s28, 3
	s_cmp_lt_u32 s20, s52
	s_cselect_b64 s[58:59], s[50:51], 0
	v_lshl_add_u64 v[248:249], v[248:249], 0, s[58:59]
	global_load_dwordx4 v[110:113], v[248:249], off offset:16
	global_load_dwordx4 v[106:109], v[248:249], off
	ds_read_b128 v[216:219], v173 offset:0
	ds_read_b128 v[220:223], v173 offset:64
	ds_read_b128 v[224:227], v173 offset:128
	ds_read_b128 v[228:231], v173 offset:192
	v_fmac_f32_e32 v17, v152, v182
	v_fmac_f32_e32 v33, v152, v178
	v_fma_f32 v17, -v153, v178, v17
	v_fmac_f32_e32 v33, v153, v182
	v_mfma_f32_32x32x16_bf16 v[34:49], v[212:215], v[66:69], 0
	v_fmac_f32_e32 v16, v152, v17
	v_fmac_f32_e32 v32, v152, v33
	v_cvt_pk_bf16_f32 v184, v17, v33
	v_fma_f32 v16, -v153, v33, v16
	v_fmac_f32_e32 v32, v153, v17
	ds_write_b32 v172, v184 offset:64496
	v_fmac_f32_e32 v15, v152, v16
	v_fmac_f32_e32 v31, v152, v32
	v_cvt_pk_bf16_f32 v185, v16, v32
	v_fma_f32 v15, -v153, v32, v15
	v_fmac_f32_e32 v31, v153, v16
	ds_write_b32 v172, v185 offset:64224
	v_mfma_f32_32x32x16_bf16 v[50:65], v[212:215], v[74:77], 0
	v_fmac_f32_e32 v14, v152, v15
	v_fmac_f32_e32 v30, v152, v31
	v_cvt_pk_bf16_f32 v184, v15, v31
	v_fma_f32 v14, -v153, v31, v14
	v_fmac_f32_e32 v30, v153, v15
	ds_write_b32 v172, v184 offset:63952
	v_fmac_f32_e32 v13, v152, v14
	v_fmac_f32_e32 v29, v152, v30
	v_cvt_pk_bf16_f32 v185, v14, v30
	v_fma_f32 v13, -v153, v30, v13
	v_fmac_f32_e32 v29, v153, v14
	ds_write_b32 v172, v185 offset:63680
	s_waitcnt lgkmcnt(4)
	v_mfma_f32_16x16x32_bf16 v[232:235], v[82:85], v[216:219], 0
	v_fmac_f32_e32 v12, v152, v13
	v_fmac_f32_e32 v28, v152, v29
	v_cvt_pk_bf16_f32 v184, v13, v29
	v_fma_f32 v12, -v153, v29, v12
	v_fmac_f32_e32 v28, v153, v13
	ds_write_b32 v172, v184 offset:63408
	v_mfma_f32_16x16x32_bf16 v[232:235], v[86:89], v[220:223], v[232:235]
	v_fmac_f32_e32 v11, v152, v12
	v_fmac_f32_e32 v27, v152, v28
	v_cvt_pk_bf16_f32 v185, v12, v28
	v_fma_f32 v11, -v153, v28, v11
	v_fmac_f32_e32 v27, v153, v12
	ds_write_b32 v172, v185 offset:63136
	v_mfma_f32_16x16x32_bf16 v[232:235], v[90:93], v[224:227], v[232:235]
	v_fmac_f32_e32 v10, v152, v11
	v_fmac_f32_e32 v26, v152, v27
	v_cvt_pk_bf16_f32 v184, v11, v27
	v_fma_f32 v10, -v153, v27, v10
	v_fmac_f32_e32 v26, v153, v11
	ds_write_b32 v172, v184 offset:62864
	v_mfma_f32_16x16x32_bf16 v[232:235], v[94:97], v[228:231], v[232:235]
	v_fmac_f32_e32 v9, v152, v10
	v_fmac_f32_e32 v25, v152, v26
	v_cvt_pk_bf16_f32 v185, v10, v26
	v_fma_f32 v9, -v153, v26, v9
	v_fmac_f32_e32 v25, v153, v10
	ds_write_b32 v172, v185 offset:62592
	v_fmac_f32_e32 v8, v152, v9
	v_fmac_f32_e32 v24, v152, v25
	v_cvt_pk_bf16_f32 v184, v9, v25
	v_fma_f32 v8, -v153, v25, v8
	v_fmac_f32_e32 v24, v153, v9
	ds_write_b32 v172, v184 offset:62320
	v_fmac_f32_e32 v7, v152, v8
	v_fmac_f32_e32 v23, v152, v24
	v_cvt_pk_bf16_f32 v185, v8, v24
	v_fma_f32 v7, -v153, v24, v7
	v_fmac_f32_e32 v23, v153, v8
	ds_write_b32 v172, v185 offset:62048
	global_store_dwordx4 v[240:241], v[232:235], off
	v_lshl_add_u64 v[240:241], v[240:241], 0, s[50:51]
	v_fmac_f32_e32 v6, v152, v7
	v_fmac_f32_e32 v22, v152, v23
	v_cvt_pk_bf16_f32 v184, v7, v23
	v_fma_f32 v6, -v153, v23, v6
	v_fmac_f32_e32 v22, v153, v7
	ds_write_b32 v172, v184 offset:61776
	v_fmac_f32_e32 v5, v152, v6
	v_fmac_f32_e32 v21, v152, v22
	v_cvt_pk_bf16_f32 v185, v6, v22
	v_fma_f32 v5, -v153, v22, v5
	v_fmac_f32_e32 v21, v153, v6
	ds_write_b32 v172, v185 offset:61504
	v_fmac_f32_e32 v4, v152, v5
	v_fmac_f32_e32 v20, v152, v21
	v_cvt_pk_bf16_f32 v184, v5, v21
	v_fma_f32 v4, -v153, v21, v4
	v_fmac_f32_e32 v20, v153, v5
	ds_write_b32 v172, v184 offset:61232
	v_fmac_f32_e32 v3, v152, v4
	v_fmac_f32_e32 v19, v152, v20
	v_cvt_pk_bf16_f32 v185, v4, v20
	v_fma_f32 v3, -v153, v20, v3
	v_fmac_f32_e32 v19, v153, v4
	ds_write_b32 v172, v185 offset:60960
	v_fma_f32 v182, v152, v3, v2
	v_fma_f32 v178, v152, v19, v18
	v_cvt_pk_bf16_f32 v184, v3, v19
	v_fma_f32 v182, -v153, v19, v182
	v_fmac_f32_e32 v178, v153, v3
	ds_write_b32 v172, v184 offset:60688
	v_cvt_pk_bf16_f32 v185, v182, v178
	ds_write_b32 v172, v185 offset:60416
	s_waitcnt lgkmcnt(0)
	s_barrier
	s_add_u32 s28, s28, 1
	s_cmp_lt_u32 s28, s52
	s_cbranch_scc1 .LS5Q_loopr0d1
	s_branch .LS5Q_epi

.LS5Q_wr0d0e:
	s_waitcnt vmcnt(4)
	v_cvt_pk_bf16_f32 v212, v102, v103
	v_cvt_pk_bf16_f32 v213, v104, v105
	v_cvt_pk_bf16_f32 v214, v98, v99
	v_cvt_pk_bf16_f32 v215, v100, v101
	s_add_u32 s20, s28, 3
	s_cmp_lt_u32 s20, s52
	s_cselect_b64 s[58:59], s[50:51], 0
	v_lshl_add_u64 v[248:249], v[248:249], 0, s[58:59]
	global_load_dwordx4 v[98:101], v[248:249], off offset:16
	global_load_dwordx4 v[102:105], v[248:249], off
	ds_read_b128 v[216:219], v173 offset:60416
	ds_read_b128 v[220:223], v173 offset:60480
	ds_read_b128 v[224:227], v173 offset:60544
	ds_read_b128 v[228:231], v173 offset:60608
	v_fmac_f32_e32 v34, v152, v182
	v_fmac_f32_e32 v50, v152, v178
	v_fma_f32 v34, -v153, v178, v34
	v_fmac_f32_e32 v50, v153, v182
	v_mfma_f32_32x32x16_bf16 v[2:17], v[212:215], v[66:69], 0
	v_fmac_f32_e32 v35, v152, v34
	v_fmac_f32_e32 v51, v152, v50
	v_cvt_pk_bf16_f32 v184, v34, v50
	v_fma_f32 v35, -v153, v50, v35
	v_fmac_f32_e32 v51, v153, v34
	ds_write_b32 v172, v184 offset:0
	v_fmac_f32_e32 v36, v152, v35
	v_fmac_f32_e32 v52, v152, v51
	v_cvt_pk_bf16_f32 v185, v35, v51
	v_fma_f32 v36, -v153, v51, v36
	v_fmac_f32_e32 v52, v153, v35
	ds_write_b32 v172, v185 offset:272
	v_mfma_f32_32x32x16_bf16 v[18:33], v[212:215], v[74:77], 0
	v_fmac_f32_e32 v37, v152, v36
	v_fmac_f32_e32 v53, v152, v52
	v_cvt_pk_bf16_f32 v184, v36, v52
	v_fma_f32 v37, -v153, v52, v37
	v_fmac_f32_e32 v53, v153, v36
	ds_write_b32 v172, v184 offset:544
	v_fmac_f32_e32 v38, v152, v37
	v_fmac_f32_e32 v54, v152, v53
	v_cvt_pk_bf16_f32 v185, v37, v53
	v_fma_f32 v38, -v153, v53, v38
	v_fmac_f32_e32 v54, v153, v37
	ds_write_b32 v172, v185 offset:816
	s_waitcnt lgkmcnt(4)
	v_mfma_f32_16x16x32_bf16 v[232:235], v[82:85], v[216:219], 0
	v_fmac_f32_e32 v39, v152, v38
	v_fmac_f32_e32 v55, v152, v54
	v_cvt_pk_bf16_f32 v184, v38, v54
	v_fma_f32 v39, -v153, v54, v39
	v_fmac_f32_e32 v55, v153, v38
	ds_write_b32 v172, v184 offset:1088
	v_mfma_f32_16x16x32_bf16 v[232:235], v[86:89], v[220:223], v[232:235]
	v_fmac_f32_e32 v40, v152, v39
	v_fmac_f32_e32 v56, v152, v55
	v_cvt_pk_bf16_f32 v185, v39, v55
	v_fma_f32 v40, -v153, v55, v40
	v_fmac_f32_e32 v56, v153, v39
	ds_write_b32 v172, v185 offset:1360
	v_mfma_f32_16x16x32_bf16 v[232:235], v[90:93], v[224:227], v[232:235]
	v_fmac_f32_e32 v41, v152, v40
	v_fmac_f32_e32 v57, v152, v56
	v_cvt_pk_bf16_f32 v184, v40, v56
	v_fma_f32 v41, -v153, v56, v41
	v_fmac_f32_e32 v57, v153, v40
	ds_write_b32 v172, v184 offset:1632
	v_mfma_f32_16x16x32_bf16 v[232:235], v[94:97], v[228:231], v[232:235]
	v_fmac_f32_e32 v42, v152, v41
	v_fmac_f32_e32 v58, v152, v57
	v_cvt_pk_bf16_f32 v185, v41, v57
	v_fma_f32 v42, -v153, v57, v42
	v_fmac_f32_e32 v58, v153, v41
	ds_write_b32 v172, v185 offset:1904
	v_fmac_f32_e32 v43, v152, v42
	v_fmac_f32_e32 v59, v152, v58
	v_cvt_pk_bf16_f32 v184, v42, v58
	v_fma_f32 v43, -v153, v58, v43
	v_fmac_f32_e32 v59, v153, v42
	ds_write_b32 v172, v184 offset:2176
	v_fmac_f32_e32 v44, v152, v43
	v_fmac_f32_e32 v60, v152, v59
	v_cvt_pk_bf16_f32 v185, v43, v59
	v_fma_f32 v44, -v153, v59, v44
	v_fmac_f32_e32 v60, v153, v43
	ds_write_b32 v172, v185 offset:2448
	s_cmp_eq_u32 s28, 0
	s_cbranch_scc1 .LS5Q_nstr0d0e
	global_store_dwordx4 v[240:241], v[232:235], off
	v_lshl_add_u64 v[240:241], v[240:241], 0, s[50:51]
.LS5Q_nstr0d0e:
	v_fmac_f32_e32 v45, v152, v44
	v_fmac_f32_e32 v61, v152, v60
	v_cvt_pk_bf16_f32 v184, v44, v60
	v_fma_f32 v45, -v153, v60, v45
	v_fmac_f32_e32 v61, v153, v44
	ds_write_b32 v172, v184 offset:2720
	v_fmac_f32_e32 v46, v152, v45
	v_fmac_f32_e32 v62, v152, v61
	v_cvt_pk_bf16_f32 v185, v45, v61
	v_fma_f32 v46, -v153, v61, v46
	v_fmac_f32_e32 v62, v153, v45
	ds_write_b32 v172, v185 offset:2992
	v_fmac_f32_e32 v47, v152, v46
	v_fmac_f32_e32 v63, v152, v62
	v_cvt_pk_bf16_f32 v184, v46, v62
	v_fma_f32 v47, -v153, v62, v47
	v_fmac_f32_e32 v63, v153, v46
	ds_write_b32 v172, v184 offset:3264
	v_fmac_f32_e32 v48, v152, v47
	v_fmac_f32_e32 v64, v152, v63
	v_cvt_pk_bf16_f32 v185, v47, v63
	v_fma_f32 v48, -v153, v63, v48
	v_fmac_f32_e32 v64, v153, v47
	ds_write_b32 v172, v185 offset:3536
	v_fma_f32 v182, v152, v48, v49
	v_fma_f32 v178, v152, v64, v65
	v_cvt_pk_bf16_f32 v184, v48, v64
	v_fma_f32 v182, -v153, v64, v182
	v_fmac_f32_e32 v178, v153, v48
	ds_write_b32 v172, v184 offset:3808
	v_cvt_pk_bf16_f32 v185, v182, v178
	ds_write_b32 v172, v185 offset:4080
	s_waitcnt lgkmcnt(0)
	s_barrier
	s_add_u32 s28, s28, 1
	s_cmp_lt_u32 s28, 3
	s_cbranch_scc0 .LS5Q_wr0d0o
	s_waitcnt vmcnt(2)
.LS5Q_wr0d0o:
	s_waitcnt vmcnt(4)
	v_cvt_pk_bf16_f32 v212, v106, v107
	v_cvt_pk_bf16_f32 v213, v108, v109
	v_cvt_pk_bf16_f32 v214, v110, v111
	v_cvt_pk_bf16_f32 v215, v112, v113
	s_add_u32 s20, s28, 3
	s_cmp_lt_u32 s20, s52
	s_cselect_b64 s[58:59], s[50:51], 0
	v_lshl_add_u64 v[248:249], v[248:249], 0, s[58:59]
	global_load_dwordx4 v[110:113], v[248:249], off offset:16
	global_load_dwordx4 v[106:109], v[248:249], off
	ds_read_b128 v[216:219], v173 offset:0
	ds_read_b128 v[220:223], v173 offset:64
	ds_read_b128 v[224:227], v173 offset:128
	ds_read_b128 v[228:231], v173 offset:192
	v_fmac_f32_e32 v2, v152, v182
	v_fmac_f32_e32 v18, v152, v178
	v_fma_f32 v2, -v153, v178, v2
	v_fmac_f32_e32 v18, v153, v182
	v_mfma_f32_32x32x16_bf16 v[34:49], v[212:215], v[66:69], 0
	v_fmac_f32_e32 v3, v152, v2
	v_fmac_f32_e32 v19, v152, v18
	v_cvt_pk_bf16_f32 v184, v2, v18
	v_fma_f32 v3, -v153, v18, v3
	v_fmac_f32_e32 v19, v153, v2
	ds_write_b32 v172, v184 offset:60416
	v_fmac_f32_e32 v4, v152, v3
	v_fmac_f32_e32 v20, v152, v19
	v_cvt_pk_bf16_f32 v185, v3, v19
	v_fma_f32 v4, -v153, v19, v4
	v_fmac_f32_e32 v20, v153, v3
	ds_write_b32 v172, v185 offset:60688
	v_mfma_f32_32x32x16_bf16 v[50:65], v[212:215], v[74:77], 0
	v_fmac_f32_e32 v5, v152, v4
	v_fmac_f32_e32 v21, v152, v20
	v_cvt_pk_bf16_f32 v184, v4, v20
	v_fma_f32 v5, -v153, v20, v5
	v_fmac_f32_e32 v21, v153, v4
	ds_write_b32 v172, v184 offset:60960
	v_fmac_f32_e32 v6, v152, v5
	v_fmac_f32_e32 v22, v152, v21
	v_cvt_pk_bf16_f32 v185, v5, v21
	v_fma_f32 v6, -v153, v21, v6
	v_fmac_f32_e32 v22, v153, v5
	ds_write_b32 v172, v185 offset:61232
	s_waitcnt lgkmcnt(4)
	v_mfma_f32_16x16x32_bf16 v[232:235], v[82:85], v[216:219], 0
	v_fmac_f32_e32 v7, v152, v6
	v_fmac_f32_e32 v23, v152, v22
	v_cvt_pk_bf16_f32 v184, v6, v22
	v_fma_f32 v7, -v153, v22, v7
	v_fmac_f32_e32 v23, v153, v6
	ds_write_b32 v172, v184 offset:61504
	v_mfma_f32_16x16x32_bf16 v[232:235], v[86:89], v[220:223], v[232:235]
	v_fmac_f32_e32 v8, v152, v7
	v_fmac_f32_e32 v24, v152, v23
	v_cvt_pk_bf16_f32 v185, v7, v23
	v_fma_f32 v8, -v153, v23, v8
	v_fmac_f32_e32 v24, v153, v7
	ds_write_b32 v172, v185 offset:61776
	v_mfma_f32_16x16x32_bf16 v[232:235], v[90:93], v[224:227], v[232:235]
	v_fmac_f32_e32 v9, v152, v8
	v_fmac_f32_e32 v25, v152, v24
	v_cvt_pk_bf16_f32 v184, v8, v24
	v_fma_f32 v9, -v153, v24, v9
	v_fmac_f32_e32 v25, v153, v8
	ds_write_b32 v172, v184 offset:62048
	v_mfma_f32_16x16x32_bf16 v[232:235], v[94:97], v[228:231], v[232:235]
	v_fmac_f32_e32 v10, v152, v9
	v_fmac_f32_e32 v26, v152, v25
	v_cvt_pk_bf16_f32 v185, v9, v25
	v_fma_f32 v10, -v153, v25, v10
	v_fmac_f32_e32 v26, v153, v9
	ds_write_b32 v172, v185 offset:62320
	v_fmac_f32_e32 v11, v152, v10
	v_fmac_f32_e32 v27, v152, v26
	v_cvt_pk_bf16_f32 v184, v10, v26
	v_fma_f32 v11, -v153, v26, v11
	v_fmac_f32_e32 v27, v153, v10
	ds_write_b32 v172, v184 offset:62592
	v_fmac_f32_e32 v12, v152, v11
	v_fmac_f32_e32 v28, v152, v27
	v_cvt_pk_bf16_f32 v185, v11, v27
	v_fma_f32 v12, -v153, v27, v12
	v_fmac_f32_e32 v28, v153, v11
	ds_write_b32 v172, v185 offset:62864
	global_store_dwordx4 v[240:241], v[232:235], off
	v_lshl_add_u64 v[240:241], v[240:241], 0, s[50:51]
	v_fmac_f32_e32 v13, v152, v12
	v_fmac_f32_e32 v29, v152, v28
	v_cvt_pk_bf16_f32 v184, v12, v28
	v_fma_f32 v13, -v153, v28, v13
	v_fmac_f32_e32 v29, v153, v12
	ds_write_b32 v172, v184 offset:63136
	v_fmac_f32_e32 v14, v152, v13
	v_fmac_f32_e32 v30, v152, v29
	v_cvt_pk_bf16_f32 v185, v13, v29
	v_fma_f32 v14, -v153, v29, v14
	v_fmac_f32_e32 v30, v153, v13
	ds_write_b32 v172, v185 offset:63408
	v_fmac_f32_e32 v15, v152, v14
	v_fmac_f32_e32 v31, v152, v30
	v_cvt_pk_bf16_f32 v184, v14, v30
	v_fma_f32 v15, -v153, v30, v15
	v_fmac_f32_e32 v31, v153, v14
	ds_write_b32 v172, v184 offset:63680
	v_fmac_f32_e32 v16, v152, v15
	v_fmac_f32_e32 v32, v152, v31
	v_cvt_pk_bf16_f32 v185, v15, v31
	v_fma_f32 v16, -v153, v31, v16
	v_fmac_f32_e32 v32, v153, v15
	ds_write_b32 v172, v185 offset:63952
	v_fma_f32 v182, v152, v16, v17
	v_fma_f32 v178, v152, v32, v33
	v_cvt_pk_bf16_f32 v184, v16, v32
	v_fma_f32 v182, -v153, v32, v182
	v_fmac_f32_e32 v178, v153, v16
	ds_write_b32 v172, v184 offset:64224
	v_cvt_pk_bf16_f32 v185, v182, v178
	ds_write_b32 v172, v185 offset:64496
	s_waitcnt lgkmcnt(0)
	s_barrier
	s_add_u32 s28, s28, 1
	s_cmp_lt_u32 s28, s52
	s_cbranch_scc1 .LS5Q_loopr0d0
	s_branch .LS5Q_epi
.LS5Q_epi:
	ds_read_b128 v[216:219], v173 offset:60416
	ds_read_b128 v[220:223], v173 offset:60480
	ds_read_b128 v[224:227], v173 offset:60544
	ds_read_b128 v[228:231], v173 offset:60608
	s_waitcnt lgkmcnt(0)
	v_mfma_f32_16x16x32_bf16 v[232:235], v[82:85], v[216:219], 0
	v_mfma_f32_16x16x32_bf16 v[232:235], v[86:89], v[220:223], v[232:235]
	v_mfma_f32_16x16x32_bf16 v[232:235], v[90:93], v[224:227], v[232:235]
	v_mfma_f32_16x16x32_bf16 v[232:235], v[94:97], v[228:231], v[232:235]
	s_nop 7
	global_store_dwordx4 v[240:241], v[232:235], off
.LS5Q_done:
.LBB0_106:
	s_or_b64 exec, exec, s[2:3]
	s_and_saveexec_b64 s[2:3], s[44:45]
	s_cbranch_execz .LBB0_91
	v_readlane_b32 s4, v251, 12
	v_readlane_b32 s5, v251, 13
	s_nop 1
	v_lshl_add_u64 v[2:3], v[150:151], 2, s[4:5]
	v_add_co_u32_e32 v4, vcc, 0x4000, v2
	global_store_dword v[2:3], v182, off
	s_nop 0
	v_addc_co_u32_e32 v5, vcc, 0, v3, vcc
	global_store_dword v[4:5], v178, off
	global_store_dword v[2:3], v180, off offset:128
	global_store_dword v[4:5], v176, off offset:128
	s_branch .LBB0_91
